# gla_lr_block K loop: the six loads of each half-iteration issued together behind counted waits (on top of the gMLP / out-GEMM / row-pass changes)
# speedup vs baseline: 1.0325x; 1.0017x over previous
.LBB0_284:
	v_add_u32_e32 v54, s11, v40
	v_ashrrev_i32_e32 v55, 31, v54
	v_lshlrev_b64 v[50:51], 1, v[54:55]
	v_lshl_add_u64 v[56:57], v[36:37], 0, v[50:51]
	v_lshl_add_u64 v[42:43], v[32:33], 0, v[50:51]
	v_lshl_add_u64 v[46:47], v[34:35], 0, v[50:51]
	global_load_dwordx4 v[50:53], v[56:57], off
	s_add_i32 s11, s11, 64
	global_load_dwordx4 v[42:45], v[42:43], off
	s_cmpk_lg_i32 s11, 0x100
	global_load_dwordx4 v[46:49], v[46:47], off
	v_add_co_u32_e32 v204, vcc, s33, v56
	s_nop 1
	v_addc_co_u32_e32 v205, vcc, 0, v57, vcc
	global_load_dwordx4 v[192:195], v[204:205], off
	v_add_co_u32_e32 v206, vcc, s39, v56
	s_nop 1
	v_addc_co_u32_e32 v207, vcc, 0, v57, vcc
	global_load_dwordx4 v[196:199], v[206:207], off
	v_add_co_u32_e32 v208, vcc, s40, v56
	s_nop 1
	v_addc_co_u32_e32 v209, vcc, 0, v57, vcc
	global_load_dwordx4 v[200:203], v[208:209], off
	s_waitcnt vmcnt(4)
	v_mfma_f32_16x16x32_bf16 v[28:31], v[50:53], v[42:45], v[28:31]
	s_waitcnt vmcnt(3)
	v_mfma_f32_16x16x32_bf16 v[24:27], v[50:53], v[46:49], v[24:27]
	s_waitcnt vmcnt(2)
	v_mfma_f32_16x16x32_bf16 v[16:19], v[192:195], v[42:45], v[16:19]
	v_mfma_f32_16x16x32_bf16 v[20:23], v[192:195], v[46:49], v[20:23]
	s_waitcnt vmcnt(1)
	v_mfma_f32_16x16x32_bf16 v[8:11], v[196:199], v[42:45], v[8:11]
	v_mfma_f32_16x16x32_bf16 v[12:15], v[196:199], v[46:49], v[12:15]
	s_waitcnt vmcnt(0)
	v_mfma_f32_16x16x32_bf16 v[0:3], v[200:203], v[42:45], v[0:3]
	v_add_u32_e32 v42, 32, v54
	v_ashrrev_i32_e32 v43, 31, v42
	v_mfma_f32_16x16x32_bf16 v[4:7], v[200:203], v[46:49], v[4:7]
	v_lshlrev_b64 v[50:51], 1, v[42:43]
	v_lshl_add_u64 v[54:55], v[36:37], 0, v[50:51]
	v_lshl_add_u64 v[42:43], v[32:33], 0, v[50:51]
	v_lshl_add_u64 v[46:47], v[34:35], 0, v[50:51]
	global_load_dwordx4 v[50:53], v[54:55], off
	s_nop 0
	global_load_dwordx4 v[42:45], v[42:43], off
	s_nop 0
	global_load_dwordx4 v[46:49], v[46:47], off
	v_add_co_u32_e32 v204, vcc, s33, v54
	s_nop 1
	v_addc_co_u32_e32 v205, vcc, 0, v55, vcc
	global_load_dwordx4 v[192:195], v[204:205], off
	v_add_co_u32_e32 v206, vcc, s39, v54
	s_nop 1
	v_addc_co_u32_e32 v207, vcc, 0, v55, vcc
	global_load_dwordx4 v[196:199], v[206:207], off
	v_add_co_u32_e32 v208, vcc, s40, v54
	s_nop 1
	v_addc_co_u32_e32 v209, vcc, 0, v55, vcc
	global_load_dwordx4 v[200:203], v[208:209], off
	s_waitcnt vmcnt(4)
	v_mfma_f32_16x16x32_bf16 v[28:31], v[50:53], v[42:45], v[28:31]
	s_waitcnt vmcnt(3)
	v_mfma_f32_16x16x32_bf16 v[24:27], v[50:53], v[46:49], v[24:27]
	s_waitcnt vmcnt(2)
	v_mfma_f32_16x16x32_bf16 v[16:19], v[192:195], v[42:45], v[16:19]
	v_mfma_f32_16x16x32_bf16 v[20:23], v[192:195], v[46:49], v[20:23]
	s_waitcnt vmcnt(1)
	v_mfma_f32_16x16x32_bf16 v[8:11], v[196:199], v[42:45], v[8:11]
	v_mfma_f32_16x16x32_bf16 v[12:15], v[196:199], v[46:49], v[12:15]
	s_waitcnt vmcnt(0)
	v_mfma_f32_16x16x32_bf16 v[0:3], v[200:203], v[42:45], v[0:3]
	v_mfma_f32_16x16x32_bf16 v[4:7], v[200:203], v[46:49], v[4:7]
	s_cbranch_scc1 .LBB0_284
	v_lshlrev_b32_e32 v32, 9, v39
	v_lshlrev_b32_e32 v33, 2, v38
	v_readlane_b32 s11, v255, 36
	s_waitcnt lgkmcnt(0)
	s_barrier
	s_nop 0
	v_add3_u32 v32, s11, v32, v33
	ds_write2_b32 v32, v28, v24 offset1:16
	ds_write2_b32 v32, v29, v25 offset0:32 offset1:48
	ds_write2_b32 v32, v30, v26 offset0:64 offset1:80
	ds_write2_b32 v32, v31, v27 offset0:96 offset1:112
	v_add_u32_e32 v24, 0x800, v32
	ds_write2_b32 v24, v16, v20 offset1:16
	ds_write2_b32 v24, v17, v21 offset0:32 offset1:48
	ds_write2_b32 v24, v18, v22 offset0:64 offset1:80
	ds_write2_b32 v24, v19, v23 offset0:96 offset1:112
	v_add_u32_e32 v16, 0x1000, v32
	ds_write2_b32 v16, v8, v12 offset1:16
	ds_write2_b32 v16, v9, v13 offset0:32 offset1:48
	ds_write2_b32 v16, v10, v14 offset0:64 offset1:80
	ds_write2_b32 v16, v11, v15 offset0:96 offset1:112
	v_add_u32_e32 v8, 0x1800, v32
	ds_write2_b32 v8, v0, v4 offset1:16
	ds_write2_b32 v8, v1, v5 offset0:32 offset1:48
	ds_write2_b32 v8, v2, v6 offset0:64 offset1:80
	ds_write2_b32 v8, v3, v7 offset0:96 offset1:112
	v_mov_b32_e32 v0, v65
	s_waitcnt lgkmcnt(0)
	s_barrier
	s_nop 0
	v_add_u32_e32 v0, v0, v190
	v_lshl_add_u32 v16, v0, 4, 0
	ds_read_b128 v[0:3], v16
	ds_read_b128 v[4:7], v16 offset:8192
	ds_read_b128 v[8:11], v16 offset:16384
	s_waitcnt lgkmcnt(2)
	v_pk_add_f32 v[2:3], v[2:3], 0 op_sel_hi:[1,0]
	v_pk_add_f32 v[12:13], v[0:1], 0 op_sel_hi:[1,0]
	s_waitcnt lgkmcnt(1)
	v_pk_add_f32 v[6:7], v[2:3], v[6:7]
	ds_read_b128 v[0:3], v16 offset:24576
	v_pk_add_f32 v[12:13], v[12:13], v[4:5]
	s_waitcnt lgkmcnt(1)
	v_pk_add_f32 v[10:11], v[6:7], v[10:11]
	ds_read_b128 v[4:7], v16 offset:32768
	v_pk_add_f32 v[8:9], v[12:13], v[8:9]
	s_waitcnt lgkmcnt(1)
	v_pk_add_f32 v[10:11], v[10:11], v[2:3]
	v_pk_add_f32 v[12:13], v[8:9], v[0:1]
	ds_read_b128 v[0:3], v16 offset:40960
	s_waitcnt lgkmcnt(1)
	v_pk_add_f32 v[14:15], v[10:11], v[6:7]
	ds_read_b128 v[6:9], v16 offset:49152
	v_pk_add_f32 v[4:5], v[12:13], v[4:5]
	ds_read_b128 v[10:13], v16 offset:57344
	s_waitcnt lgkmcnt(2)
	v_pk_add_f32 v[2:3], v[14:15], v[2:3]
	v_pk_add_f32 v[0:1], v[4:5], v[0:1]
	s_waitcnt lgkmcnt(1)
	v_pk_add_f32 v[2:3], v[2:3], v[8:9]
	v_pk_add_f32 v[0:1], v[0:1], v[6:7]
	s_waitcnt lgkmcnt(0)
	v_pk_add_f32 v[2:3], v[2:3], v[12:13]
	v_pk_add_f32 v[0:1], v[0:1], v[10:11]
	v_add_u32_e32 v4, 0x19800, v16
	ds_write_b128 v4, v[0:3]
	s_waitcnt lgkmcnt(0)
	s_barrier
